# attention block boundaries combined: head counted waits + tail vmcnt(12) + gate-load hoist + tail PV counted LDS waits
# speedup vs baseline: 1.0128x; 1.0128x over previous
.LBB0_420:
	v_or_b32_e32 v120, v180, v179
	v_lshlrev_b32_e32 v120, 1, v120
	v_add_u32_e32 v121, 0x4000, v120
	v_add_u32_e32 v122, 0x8000, v120
	v_add_u32_e32 v123, 0xc000, v120
	global_load_dwordx2 v[176:177], v120, s[6:7]
	global_load_dwordx2 v[174:175], v121, s[6:7]
	global_load_dwordx2 v[172:173], v122, s[6:7]
	global_load_dwordx2 v[170:171], v123, s[6:7]
	global_load_dwordx2 v[168:169], v120, s[6:7] offset:64
	global_load_dwordx2 v[166:167], v121, s[6:7] offset:64
	global_load_dwordx2 v[164:165], v122, s[6:7] offset:64
	global_load_dwordx2 v[162:163], v123, s[6:7] offset:64
	global_load_dwordx2 v[128:129], v120, s[6:7] offset:128
	global_load_dwordx2 v[126:127], v121, s[6:7] offset:128
	global_load_dwordx2 v[124:125], v122, s[6:7] offset:128
	global_load_dwordx2 v[122:123], v123, s[6:7] offset:128
	global_load_dwordx2 v[120:121], v120, s[6:7] offset:192
	v_cndmask_b32_e64 v114, v114, v182, s[4:5]
	v_mul_f32_e32 v114, 0xbe0293ee, v114
	v_fmamk_f32 v50, v50, 0x3e0293ee, v114
	v_fmamk_f32 v51, v51, 0x3e0293ee, v114
	v_exp_f32_e32 v50, v50
	v_fmamk_f32 v52, v52, 0x3e0293ee, v114
	v_fmamk_f32 v119, v65, 0x3e0293ee, v114
	v_exp_f32_e32 v65, v51
	v_fmamk_f32 v53, v53, 0x3e0293ee, v114
	v_exp_f32_e32 v51, v52
	v_fmamk_f32 v54, v54, 0x3e0293ee, v114
	v_fmamk_f32 v55, v55, 0x3e0293ee, v114
	v_fmamk_f32 v56, v56, 0x3e0293ee, v114
	v_fmamk_f32 v57, v57, 0x3e0293ee, v114
	v_fmamk_f32 v58, v58, 0x3e0293ee, v114
	v_fmamk_f32 v59, v59, 0x3e0293ee, v114
	v_fmamk_f32 v60, v60, 0x3e0293ee, v114
	v_fmamk_f32 v115, v61, 0x3e0293ee, v114
	v_fmamk_f32 v116, v62, 0x3e0293ee, v114
	v_fmamk_f32 v117, v63, 0x3e0293ee, v114
	v_fmamk_f32 v118, v64, 0x3e0293ee, v114
	v_fmamk_f32 v82, v82, 0x3e0293ee, v114
	v_fmamk_f32 v83, v83, 0x3e0293ee, v114
	v_fmamk_f32 v84, v84, 0x3e0293ee, v114
	v_fmamk_f32 v85, v85, 0x3e0293ee, v114
	v_fmamk_f32 v86, v86, 0x3e0293ee, v114
	v_fmamk_f32 v87, v87, 0x3e0293ee, v114
	v_fmamk_f32 v88, v88, 0x3e0293ee, v114
	v_fmamk_f32 v89, v89, 0x3e0293ee, v114
	v_fmamk_f32 v90, v90, 0x3e0293ee, v114
	v_fmamk_f32 v91, v91, 0x3e0293ee, v114
	v_fmamk_f32 v92, v92, 0x3e0293ee, v114
	v_fmamk_f32 v93, v93, 0x3e0293ee, v114
	v_fmamk_f32 v94, v94, 0x3e0293ee, v114
	v_exp_f32_e32 v64, v53
	v_fmamk_f32 v95, v95, 0x3e0293ee, v114
	v_fmamk_f32 v96, v96, 0x3e0293ee, v114
	v_fmac_f32_e32 v114, 0x3e0293ee, v97
	v_exp_f32_e32 v52, v54
	v_exp_f32_e32 v97, v114
	v_add_f32_e32 v114, 0, v50
	v_exp_f32_e32 v63, v55
	v_add_f32_e32 v114, v65, v114
	v_exp_f32_e32 v53, v56
	v_add_f32_e32 v114, v51, v114
	v_exp_f32_e32 v62, v57
	v_add_f32_e32 v114, v64, v114
	v_exp_f32_e32 v54, v58
	v_add_f32_e32 v114, v52, v114
	v_exp_f32_e32 v61, v59
	v_add_f32_e32 v114, v63, v114
	v_exp_f32_e32 v55, v60
	v_add_f32_e32 v114, v53, v114
	v_exp_f32_e32 v60, v115
	v_add_f32_e32 v114, v62, v114
	v_exp_f32_e32 v56, v116
	v_add_f32_e32 v114, v54, v114
	v_exp_f32_e32 v59, v117
	v_add_f32_e32 v114, v61, v114
	v_exp_f32_e32 v57, v118
	v_add_f32_e32 v114, v55, v114
	v_exp_f32_e32 v58, v119
	v_add_f32_e32 v114, v60, v114
	v_exp_f32_e32 v82, v82
	v_add_f32_e32 v114, v56, v114
	v_exp_f32_e32 v83, v83
	v_add_f32_e32 v114, v59, v114
	v_exp_f32_e32 v84, v84
	v_add_f32_e32 v114, v57, v114
	v_exp_f32_e32 v85, v85
	v_add_f32_e32 v114, v58, v114
	v_exp_f32_e32 v86, v86
	v_add_f32_e32 v114, v82, v114
	v_exp_f32_e32 v87, v87
	v_add_f32_e32 v114, v83, v114
	v_exp_f32_e32 v88, v88
	v_add_f32_e32 v114, v84, v114
	v_exp_f32_e32 v89, v89
	v_add_f32_e32 v114, v85, v114
	v_exp_f32_e32 v90, v90
	v_add_f32_e32 v114, v86, v114
	v_exp_f32_e32 v91, v91
	v_add_f32_e32 v114, v87, v114
	v_exp_f32_e32 v92, v92
	v_add_f32_e32 v114, v88, v114
	v_exp_f32_e32 v93, v93
	v_add_f32_e32 v114, v89, v114
	v_exp_f32_e32 v94, v94
	v_add_f32_e32 v114, v90, v114
	v_exp_f32_e32 v95, v95
	v_add_f32_e32 v114, v91, v114
	v_exp_f32_e32 v96, v96
	v_add_f32_e32 v114, v92, v114
	v_add_f32_e32 v114, v93, v114
	v_add_f32_e32 v114, v94, v114
	v_add_f32_e32 v114, v95, v114
	v_add_f32_e32 v114, v96, v114
	v_add_f32_e32 v182, v97, v114
	v_mov_b32_e32 v183, v182
	v_cvt_pk_bf16_f32 v50, v50, v65
	v_cvt_pk_bf16_f32 v51, v51, v64
	v_cvt_pk_bf16_f32 v52, v52, v63
	v_cvt_pk_bf16_f32 v53, v53, v62
	v_cvt_pk_bf16_f32 v54, v54, v61
	v_cvt_pk_bf16_f32 v55, v55, v60
	v_cvt_pk_bf16_f32 v56, v56, v59
	v_cvt_pk_bf16_f32 v57, v57, v58
	v_cvt_pk_bf16_f32 v58, v82, v83
	v_cvt_pk_bf16_f32 v59, v84, v85
	v_cvt_pk_bf16_f32 v60, v86, v87
	v_cvt_pk_bf16_f32 v61, v88, v89
	v_cvt_pk_bf16_f32 v62, v90, v91
	v_cvt_pk_bf16_f32 v63, v92, v93
	v_cvt_pk_bf16_f32 v64, v94, v95
	v_cvt_pk_bf16_f32 v65, v96, v97
	s_nop 1
	v_permlane32_swap_b32_e32 v182, v183
	v_permlane32_swap_b32_e32 v50, v52
	v_permlane32_swap_b32_e32 v51, v53
	v_permlane32_swap_b32_e32 v54, v56
	v_permlane32_swap_b32_e32 v55, v57
	v_permlane32_swap_b32_e32 v58, v60
	v_permlane32_swap_b32_e32 v59, v61
	v_permlane32_swap_b32_e32 v62, v64
	v_permlane32_swap_b32_e32 v63, v65
	v_or_b32_e32 v82, v180, v179
	v_lshlrev_b32_e32 v82, 1, v82
	v_add_u32_e32 v83, 0x4000, v82
	v_add_u32_e32 v84, 0x8000, v82
	v_add_u32_e32 v85, 0xc000, v82
	global_load_dwordx2 v[118:119], v83, s[6:7] offset:192
	global_load_dwordx2 v[116:117], v84, s[6:7] offset:192
	global_load_dwordx2 v[114:115], v85, s[6:7] offset:192
	v_add_f32_e32 v186, v182, v183
	v_fmac_f32_e32 v186, v181, v178
	ds_read_b64_tr_b16 v[82:83], v209 offset:0x4000
	ds_read_b64_tr_b16 v[84:85], v209 offset:0x4800
	ds_read_b64_tr_b16 v[86:87], v209 offset:0x5000
	ds_read_b64_tr_b16 v[88:89], v209 offset:0x5800
	ds_read_b64_tr_b16 v[90:91], v209 offset:0x6000
	ds_read_b64_tr_b16 v[92:93], v209 offset:0x6800
	ds_read_b64_tr_b16 v[94:95], v209 offset:0x7000
	ds_read_b64_tr_b16 v[96:97], v209 offset:0x7800
	s_nop 0
	s_waitcnt lgkmcnt(6)
	v_mfma_f32_32x32x16_bf16 v[66:81], v[50:53], v[82:85], v[66:81]
	ds_read_b64_tr_b16 v[82:83], v209 offset:0x4200
	ds_read_b64_tr_b16 v[84:85], v209 offset:0x4a00
	s_waitcnt lgkmcnt(6)
	v_mfma_f32_32x32x16_bf16 v[66:81], v[54:57], v[86:89], v[66:81]
	ds_read_b64_tr_b16 v[86:87], v209 offset:0x5200
	ds_read_b64_tr_b16 v[88:89], v209 offset:0x5a00
	s_waitcnt lgkmcnt(6)
	v_mfma_f32_32x32x16_bf16 v[66:81], v[58:61], v[90:93], v[66:81]
	ds_read_b64_tr_b16 v[90:91], v209 offset:0x6200
	ds_read_b64_tr_b16 v[92:93], v209 offset:0x6a00
	ds_read_b64_tr_b16 v[178:179], v209 offset:0x7200
	ds_read_b64_tr_b16 v[180:181], v209 offset:0x7a00
	s_waitcnt lgkmcnt(8)
	v_mfma_f32_32x32x16_bf16 v[66:81], v[62:65], v[94:97], v[66:81]
	s_waitcnt lgkmcnt(6)
	v_mfma_f32_32x32x16_bf16 v[34:49], v[50:53], v[82:85], v[34:49]
	ds_read_b64_tr_b16 v[82:83], v209 offset:0x4400
	ds_read_b64_tr_b16 v[84:85], v209 offset:0x4c00
	s_waitcnt lgkmcnt(6)
	v_mfma_f32_32x32x16_bf16 v[34:49], v[54:57], v[86:89], v[34:49]
	ds_read_b64_tr_b16 v[86:87], v209 offset:0x5400
	ds_read_b64_tr_b16 v[88:89], v209 offset:0x5c00
	s_waitcnt lgkmcnt(6)
	v_mfma_f32_32x32x16_bf16 v[34:49], v[58:61], v[90:93], v[34:49]
	ds_read_b64_tr_b16 v[90:91], v209 offset:0x6400
	ds_read_b64_tr_b16 v[92:93], v209 offset:0x6c00
	ds_read_b64_tr_b16 v[94:95], v209 offset:0x7400
	ds_read_b64_tr_b16 v[96:97], v209 offset:0x7c00
	s_waitcnt lgkmcnt(8)
	v_mfma_f32_32x32x16_bf16 v[34:49], v[62:65], v[178:181], v[34:49]
	s_waitcnt lgkmcnt(6)
	v_mfma_f32_32x32x16_bf16 v[18:33], v[50:53], v[82:85], v[18:33]
	ds_read_b64_tr_b16 v[82:83], v209 offset:0x4600
	ds_read_b64_tr_b16 v[84:85], v209 offset:0x4e00
	s_waitcnt lgkmcnt(6)
	v_mfma_f32_32x32x16_bf16 v[18:33], v[54:57], v[86:89], v[18:33]
	ds_read_b64_tr_b16 v[86:87], v209 offset:0x5600
	ds_read_b64_tr_b16 v[88:89], v209 offset:0x5e00
	s_waitcnt lgkmcnt(6)
	v_mfma_f32_32x32x16_bf16 v[18:33], v[58:61], v[90:93], v[18:33]
	ds_read_b64_tr_b16 v[90:91], v209 offset:0x6600
	ds_read_b64_tr_b16 v[92:93], v209 offset:0x6e00
	ds_read_b64_tr_b16 v[182:183], v209 offset:0x7600
	ds_read_b64_tr_b16 v[184:185], v209 offset:0x7e00
	s_waitcnt lgkmcnt(8)
	v_mfma_f32_32x32x16_bf16 v[18:33], v[62:65], v[94:97], v[18:33]
	s_waitcnt lgkmcnt(6)
	v_mfma_f32_32x32x16_bf16 v[2:17], v[50:53], v[82:85], v[2:17]
	v_mov_b32_e32 v181, v186
	s_waitcnt lgkmcnt(4)
	v_mfma_f32_32x32x16_bf16 v[2:17], v[54:57], v[86:89], v[2:17]
	s_waitcnt lgkmcnt(2)
	v_mfma_f32_32x32x16_bf16 v[2:17], v[58:61], v[90:93], v[2:17]
	s_waitcnt lgkmcnt(0)
	v_mfma_f32_32x32x16_bf16 v[2:17], v[62:65], v[182:185], v[2:17]
